# attention loops: next-K LDS stores and next-V global loads moved into the PV MFMA stream (MLA + diff), V LDS stores and next-K loads in the QK stream
# speedup vs baseline: 1.0229x; 1.0096x over previous
; DI void softmax_pv(f32x16 (&sa)[2], f32x16 (&O)[4], float& m, float& l, const char* sV, int lr, int lh, bool first) {
;   float t0 = fmaxf(fmaxf(sa[0][0], sa[0][1]), sa[0][2]);
;   float t1 = fmaxf(fmaxf(sa[1][0], sa[1][1]), sa[1][2]);
; #pragma unroll
;   for (int i = 3; i < 15; i += 2) {
;     t0 = fmaxf(fmaxf(t0, sa[0][i]), sa[0][i + 1]);
;     t1 = fmaxf(fmaxf(t1, sa[1][i]), sa[1][i + 1]);
;   }
;   float tmax = fmaxf(fmaxf(t0, t1), fmaxf(sa[0][15], sa[1][15]));
;   tmax = fmaxf(tmax, __shfl_xor(tmax, 32, 64));
;   if (first || __any(tmax > SM_THR)) {
;     asm volatile("; rescale" ::: "memory");
;     const float delta = first ? tmax : fmaxf(tmax, 0.f);
;     const float alpha = __builtin_amdgcn_exp2f(-delta);
;     m += delta;
;     l *= alpha;
; #pragma unroll
;     for (int d = 0; d < 4; ++d)
; #pragma unroll
;       for (int i = 0; i < 16; ++i) O[d][i] *= alpha;
; #pragma unroll
;     for (int i = 0; i < 16; ++i) { sa[0][i] -= delta; sa[1][i] -= delta; }
;   }
; DI void diff_item(const Params& p, const GroupP& g, int l_layer, int item, char* smem, bool dry) {
;     ...
;     __syncthreads();
;     if (more) { storeK(); load_vtile(rv, vbase, Lp, (kt + 1) * 64, voffV); }
.LBB0_128:
	v_cndmask_b32_e64 v172, 0, 1, s[40:41]
	v_cmp_ne_u32_e64 s[8:9], 1, v172
	s_andn2_b64 vcc, exec, s[40:41]
	s_barrier
	s_cbranch_vccnz .LBB0_130
.LBB0_130:
	v_max3_f32 v172, v80, v81, v82
	s_nop 1
	v_max3_f32 v173, v64, v65, v66
	v_max3_f32 v172, v172, v83, v84
	v_max3_f32 v173, v173, v67, v68
	v_max3_f32 v172, v172, v85, v86
	v_max3_f32 v173, v173, v69, v70
	v_max3_f32 v172, v172, v87, v88
	v_max3_f32 v173, v173, v71, v72
	v_max3_f32 v172, v172, v89, v90
	v_max3_f32 v173, v173, v73, v74
	v_max3_f32 v172, v172, v91, v92
	v_max3_f32 v173, v173, v75, v76
	v_max_f32_e32 v174, v79, v79
	v_max_f32_e32 v175, v95, v95
	v_max3_f32 v172, v172, v93, v94
	v_max3_f32 v173, v173, v77, v78
	v_max_f32_e32 v174, v175, v174
	v_max3_f32 v172, v172, v173, v174
	ds_bpermute_b32 v173, v164, v172
	s_mov_b32 s10, 0x41000000
	s_waitcnt lgkmcnt(0)
	v_max_f32_e32 v173, v173, v173
	v_max_f32_e32 v172, v172, v173
	v_cmp_lt_f32_e32 vcc, s10, v172
	s_cbranch_vccz .LBB0_132
	v_max_f32_e32 v172, v172, v172
	v_max_f32_e32 v172, 0, v172
	v_exp_f32_e64 v174, -v172
	v_add_f32_e32 v166, v166, v172
	v_pk_add_f32 v[80:81], v[80:81], v[172:173] op_sel_hi:[1,0] neg_lo:[0,1] neg_hi:[0,1]
	v_mul_f32_e32 v163, v163, v174
	v_pk_mul_f32 v[62:63], v[62:63], v[174:175] op_sel_hi:[1,0]
	v_pk_mul_f32 v[60:61], v[60:61], v[174:175] op_sel_hi:[1,0]
	v_pk_mul_f32 v[58:59], v[58:59], v[174:175] op_sel_hi:[1,0]
	v_pk_mul_f32 v[56:57], v[56:57], v[174:175] op_sel_hi:[1,0]
	v_pk_mul_f32 v[54:55], v[54:55], v[174:175] op_sel_hi:[1,0]
	v_pk_mul_f32 v[52:53], v[52:53], v[174:175] op_sel_hi:[1,0]
	v_pk_mul_f32 v[50:51], v[50:51], v[174:175] op_sel_hi:[1,0]
	v_pk_mul_f32 v[48:49], v[48:49], v[174:175] op_sel_hi:[1,0]
	v_pk_mul_f32 v[46:47], v[46:47], v[174:175] op_sel_hi:[1,0]
	v_pk_mul_f32 v[44:45], v[44:45], v[174:175] op_sel_hi:[1,0]
	v_pk_mul_f32 v[42:43], v[42:43], v[174:175] op_sel_hi:[1,0]
	v_pk_mul_f32 v[40:41], v[40:41], v[174:175] op_sel_hi:[1,0]
	v_pk_mul_f32 v[38:39], v[38:39], v[174:175] op_sel_hi:[1,0]
	v_pk_mul_f32 v[36:37], v[36:37], v[174:175] op_sel_hi:[1,0]
	v_pk_mul_f32 v[34:35], v[34:35], v[174:175] op_sel_hi:[1,0]
	v_pk_mul_f32 v[32:33], v[32:33], v[174:175] op_sel_hi:[1,0]
	v_pk_mul_f32 v[30:31], v[30:31], v[174:175] op_sel_hi:[1,0]
	v_pk_mul_f32 v[28:29], v[28:29], v[174:175] op_sel_hi:[1,0]
	v_pk_mul_f32 v[26:27], v[26:27], v[174:175] op_sel_hi:[1,0]
	v_pk_mul_f32 v[24:25], v[24:25], v[174:175] op_sel_hi:[1,0]
	v_pk_mul_f32 v[22:23], v[22:23], v[174:175] op_sel_hi:[1,0]
	v_pk_mul_f32 v[20:21], v[20:21], v[174:175] op_sel_hi:[1,0]
	v_pk_mul_f32 v[18:19], v[18:19], v[174:175] op_sel_hi:[1,0]
	v_pk_mul_f32 v[16:17], v[16:17], v[174:175] op_sel_hi:[1,0]
	v_pk_mul_f32 v[14:15], v[14:15], v[174:175] op_sel_hi:[1,0]
	v_pk_mul_f32 v[12:13], v[12:13], v[174:175] op_sel_hi:[1,0]
	v_pk_mul_f32 v[10:11], v[10:11], v[174:175] op_sel_hi:[1,0]
	v_pk_mul_f32 v[8:9], v[8:9], v[174:175] op_sel_hi:[1,0]
	v_pk_mul_f32 v[6:7], v[6:7], v[174:175] op_sel_hi:[1,0]
	v_pk_mul_f32 v[4:5], v[4:5], v[174:175] op_sel_hi:[1,0]
	v_pk_mul_f32 v[2:3], v[2:3], v[174:175] op_sel_hi:[1,0]
	v_pk_mul_f32 v[0:1], v[0:1], v[174:175] op_sel_hi:[1,0]
	v_pk_add_f32 v[64:65], v[64:65], v[172:173] op_sel_hi:[1,0] neg_lo:[0,1] neg_hi:[0,1]
	v_pk_add_f32 v[82:83], v[82:83], v[172:173] op_sel_hi:[1,0] neg_lo:[0,1] neg_hi:[0,1]
	v_pk_add_f32 v[66:67], v[66:67], v[172:173] op_sel_hi:[1,0] neg_lo:[0,1] neg_hi:[0,1]
	v_pk_add_f32 v[84:85], v[84:85], v[172:173] op_sel_hi:[1,0] neg_lo:[0,1] neg_hi:[0,1]
	v_pk_add_f32 v[68:69], v[68:69], v[172:173] op_sel_hi:[1,0] neg_lo:[0,1] neg_hi:[0,1]
	v_pk_add_f32 v[86:87], v[86:87], v[172:173] op_sel_hi:[1,0] neg_lo:[0,1] neg_hi:[0,1]
	v_pk_add_f32 v[70:71], v[70:71], v[172:173] op_sel_hi:[1,0] neg_lo:[0,1] neg_hi:[0,1]
	v_pk_add_f32 v[88:89], v[88:89], v[172:173] op_sel_hi:[1,0] neg_lo:[0,1] neg_hi:[0,1]
	v_pk_add_f32 v[72:73], v[72:73], v[172:173] op_sel_hi:[1,0] neg_lo:[0,1] neg_hi:[0,1]
	v_pk_add_f32 v[90:91], v[90:91], v[172:173] op_sel_hi:[1,0] neg_lo:[0,1] neg_hi:[0,1]
	v_pk_add_f32 v[74:75], v[74:75], v[172:173] op_sel_hi:[1,0] neg_lo:[0,1] neg_hi:[0,1]
	v_pk_add_f32 v[92:93], v[92:93], v[172:173] op_sel_hi:[1,0] neg_lo:[0,1] neg_hi:[0,1]
	v_pk_add_f32 v[76:77], v[76:77], v[172:173] op_sel_hi:[1,0] neg_lo:[0,1] neg_hi:[0,1]
	v_pk_add_f32 v[94:95], v[94:95], v[172:173] op_sel_hi:[1,0] neg_lo:[0,1] neg_hi:[0,1]
	v_pk_add_f32 v[78:79], v[78:79], v[172:173] op_sel_hi:[1,0] neg_lo:[0,1] neg_hi:[0,1]
; #define MFMA(a, b, c) __builtin_amdgcn_mfma_f32_32x32x16_bf16((a), (b), (c), 0, 0, 0)
; DI void softmax_pv(f32x16 (&sa)[2], f32x16 (&O)[4], float& m, float& l, const char* sV, int lr, int lh, bool first) {
;     ...
;   float rsum0 = 0.f, rsum1 = 0.f;
; #pragma unroll
;   for (int i = 0; i < 16; ++i) {
;     float p0 = __builtin_amdgcn_exp2f(sa[0][i]);
;     float p1 = __builtin_amdgcn_exp2f(sa[1][i]);
;     sa[0][i] = p0;
;     sa[1][i] = p1;
;     rsum0 += p0;
;     rsum1 += p1;
;   }
;   l += rsum0 + rsum1;
;   bf16x8 pf[4];
; #pragma unroll
;   for (int g4 = 0; g4 < 4; ++g4) {
;     const int kb = g4 >> 1, s2 = g4 & 1;
;     u32x4 pp;
; #pragma unroll
;     for (int j = 0; j < 4; ++j) pp[j] = pk2(sa[kb][8 * s2 + 2 * j], sa[kb][8 * s2 + 2 * j + 1]);
;     pf[g4] = __builtin_bit_cast(bf16x8, pp);
;   }
;   const char* vrd = sV + lr * 144 + lh * 16;
;   bf16x8 vfr[4];
; #pragma unroll
;   for (int t = 0; t < 3; ++t) vfr[t] = *(const bf16x8*)(vrd + (t & 3) * (32 * 144) + (t >> 2) * 32);
;   __builtin_amdgcn_sched_group_barrier(0x100, 3, 0);
; #pragma unroll
;   for (int t = 0; t < 16; ++t) {
;     if (t + 3 < 16) {
;       vfr[(t + 3) & 3] = *(const bf16x8*)(vrd + ((t + 3) & 3) * (32 * 144) + ((t + 3) >> 2) * 32);
;       __builtin_amdgcn_sched_group_barrier(0x100, 1, 0);
;     }
;     O[t & 3] = MFMA(vfr[t & 3], pf[t >> 2], O[t & 3]);
;     __builtin_amdgcn_sched_group_barrier(0x008, 1, 0);
;   }
; DI void diff_item(const Params& p, const GroupP& g, int l_layer, int item, char* smem, bool dry) {
;     ...
;     __syncthreads();
;     if (more) { storeK(); load_vtile(rv, vbase, Lp, (kt + 1) * 64, voffV); }
.LBB0_132:
	ds_read_b128 v[192:195], v165 offset:17408
	ds_read_b128 v[196:199], v165 offset:22016
	ds_read_b128 v[202:205], v165 offset:26624
	ds_read_b128 v[206:209], v165 offset:31232
	v_exp_f32_e32 v80, v80
	v_exp_f32_e32 v81, v81
	v_exp_f32_e32 v82, v82
	v_exp_f32_e32 v83, v83
	v_exp_f32_e32 v84, v84
	v_exp_f32_e32 v85, v85
	v_exp_f32_e32 v86, v86
	v_exp_f32_e32 v87, v87
	v_cvt_pk_bf16_f32 v188, v80, v81
	v_cvt_pk_bf16_f32 v189, v82, v83
	v_cvt_pk_bf16_f32 v190, v84, v85
	v_cvt_pk_bf16_f32 v191, v86, v87
	v_exp_f32_e32 v88, v88
	v_exp_f32_e32 v89, v89
	s_waitcnt lgkmcnt(3)
	v_mfma_f32_32x32x16_bf16 v[48:63], v[192:195], v[188:191], v[48:63]
	ds_read_b128 v[192:195], v165 offset:17440
	v_exp_f32_e32 v90, v90
	v_exp_f32_e32 v91, v91
	v_exp_f32_e32 v92, v92
	v_exp_f32_e32 v93, v93
	v_exp_f32_e32 v94, v94
	v_exp_f32_e32 v95, v95
	s_waitcnt lgkmcnt(3)
	v_mfma_f32_32x32x16_bf16 v[32:47], v[196:199], v[188:191], v[32:47]
	ds_read_b128 v[196:199], v165 offset:22048
	s_add_i32 s100, s42, 2
	s_cmp_ge_i32 s100, s85
	s_cbranch_scc1 .Lpvd0_novl
	v_lshl_add_u64 v[120:121], v[150:151], 0, s[94:95]
	v_lshl_add_u64 v[124:125], v[120:121], 0, s[88:89]
	v_lshl_add_u64 v[128:129], v[124:125], 0, s[88:89]
	v_lshl_add_u64 v[132:133], v[128:129], 0, s[88:89]
	global_load_dwordx4 v[120:123], v[120:121], off
	global_load_dwordx4 v[124:127], v[124:125], off
	global_load_dwordx4 v[128:131], v[128:129], off
	global_load_dwordx4 v[132:135], v[132:133], off
.Lpvd0_novl:
	v_exp_f32_e32 v180, v72
	v_exp_f32_e32 v181, v73
	v_exp_f32_e32 v182, v74
	v_exp_f32_e32 v183, v75
	v_cvt_pk_bf16_f32 v72, v88, v89
	v_cvt_pk_bf16_f32 v73, v90, v91
	s_waitcnt lgkmcnt(3)
	v_mfma_f32_32x32x16_bf16 v[16:31], v[202:205], v[188:191], v[16:31]
	ds_read_b128 v[202:205], v165 offset:26656
	v_cvt_pk_bf16_f32 v74, v92, v93
	v_cvt_pk_bf16_f32 v75, v94, v95
	v_exp_f32_e32 v172, v64
	v_exp_f32_e32 v173, v65
	v_exp_f32_e32 v174, v66
	v_exp_f32_e32 v175, v67
	s_waitcnt lgkmcnt(3)
	v_mfma_f32_32x32x16_bf16 v[0:15], v[206:209], v[188:191], v[0:15]
	ds_read_b128 v[188:191], v165 offset:31264
	s_waitcnt vmcnt(5)
	ds_write_b128 v145, v[116:119]
	ds_write_b128 v145, v[112:115] offset:4352
	v_exp_f32_e32 v176, v68
	v_exp_f32_e32 v177, v69
	v_exp_f32_e32 v178, v70
	v_exp_f32_e32 v179, v71
	v_cvt_pk_bf16_f32 v68, v172, v173
	v_cvt_pk_bf16_f32 v69, v174, v175
	s_waitcnt lgkmcnt(5)
	v_mfma_f32_32x32x16_bf16 v[48:63], v[192:195], v[72:75], v[48:63]
	ds_read_b128 v[192:195], v165 offset:17472
	v_cvt_pk_bf16_f32 v70, v176, v177
	v_cvt_pk_bf16_f32 v71, v178, v179
	v_exp_f32_e32 v76, v76
	v_exp_f32_e32 v77, v77
	v_exp_f32_e32 v78, v78
	v_exp_f32_e32 v79, v79
	s_waitcnt lgkmcnt(5)
	v_mfma_f32_32x32x16_bf16 v[32:47], v[196:199], v[72:75], v[32:47]
	ds_read_b128 v[196:199], v165 offset:22080
	v_cvt_pk_bf16_f32 v64, v180, v181
	v_cvt_pk_bf16_f32 v65, v182, v183
	v_cvt_pk_bf16_f32 v66, v76, v77
	v_cvt_pk_bf16_f32 v67, v78, v79
	s_and_b64 vcc, exec, s[8:9]
	s_waitcnt lgkmcnt(5)
	v_mfma_f32_32x32x16_bf16 v[16:31], v[202:205], v[72:75], v[16:31]
	ds_read_b128 v[202:205], v165 offset:26688
	s_waitcnt lgkmcnt(5)
	v_mfma_f32_32x32x16_bf16 v[0:15], v[188:191], v[72:75], v[0:15]
	ds_read_b128 v[72:75], v165 offset:31296
	ds_write_b128 v145, v[136:139] offset:8704
	s_waitcnt vmcnt(4)
	ds_write_b128 v145, v[140:143] offset:13056
	s_waitcnt lgkmcnt(5)
	v_mfma_f32_32x32x16_bf16 v[48:63], v[192:195], v[68:71], v[48:63]
	ds_read_b128 v[188:191], v165 offset:17504
	s_waitcnt lgkmcnt(5)
	v_mfma_f32_32x32x16_bf16 v[32:47], v[196:199], v[68:71], v[32:47]
	ds_read_b128 v[192:195], v165 offset:22112
	s_waitcnt lgkmcnt(5)
	v_mfma_f32_32x32x16_bf16 v[16:31], v[202:205], v[68:71], v[16:31]
	ds_read_b128 v[196:199], v165 offset:26720
	s_waitcnt lgkmcnt(5)
	v_mfma_f32_32x32x16_bf16 v[0:15], v[72:75], v[68:71], v[0:15]
	ds_read_b128 v[68:71], v165 offset:31328
	s_waitcnt lgkmcnt(0)
	s_barrier
	v_mfma_f32_32x32x16_bf16 v[48:63], v[188:191], v[64:67], v[48:63]
	v_mfma_f32_32x32x16_bf16 v[32:47], v[192:195], v[64:67], v[32:47]
	v_mfma_f32_32x32x16_bf16 v[16:31], v[196:199], v[64:67], v[16:31]
	v_mfma_f32_32x32x16_bf16 v[0:15], v[68:71], v[64:67], v[0:15]
	s_branch .LBB0_121

; DI void softmax_pv(f32x16 (&sa)[2], f32x16 (&O)[4], float& m, float& l, const char* sV, int lr, int lh, bool first) {
;   float t0 = fmaxf(fmaxf(sa[0][0], sa[0][1]), sa[0][2]);
;   float t1 = fmaxf(fmaxf(sa[1][0], sa[1][1]), sa[1][2]);
; #pragma unroll
;   for (int i = 3; i < 15; i += 2) {
;     t0 = fmaxf(fmaxf(t0, sa[0][i]), sa[0][i + 1]);
;     t1 = fmaxf(fmaxf(t1, sa[1][i]), sa[1][i + 1]);
;   }
;   float tmax = fmaxf(fmaxf(t0, t1), fmaxf(sa[0][15], sa[1][15]));
;   tmax = fmaxf(tmax, __shfl_xor(tmax, 32, 64));
;   if (first || __any(tmax > SM_THR)) {
;     asm volatile("; rescale" ::: "memory");
;     const float delta = first ? tmax : fmaxf(tmax, 0.f);
;     const float alpha = __builtin_amdgcn_exp2f(-delta);
;     m += delta;
;     l *= alpha;
; #pragma unroll
;     for (int d = 0; d < 4; ++d)
; #pragma unroll
;       for (int i = 0; i < 16; ++i) O[d][i] *= alpha;
; #pragma unroll
;     for (int i = 0; i < 16; ++i) { sa[0][i] -= delta; sa[1][i] -= delta; }
;   }
; DI void mla_item(const Params& p, const GroupP& g, int item, char* smem, bool dry) {
;     ...
;     __syncthreads();
;     if (more) { storeK(); load_vtile(rv, vbase, Lp, (kt + 1) * 64, voffV); }
.LBB0_156:
	v_cndmask_b32_e64 v184, 0, 1, s[4:5]
	v_cmp_ne_u32_e64 s[74:75], 1, v184
	s_andn2_b64 vcc, exec, s[4:5]
	s_barrier
	s_cbranch_vccnz .LBB0_158
.LBB0_158:
	s_nop 3
	v_max3_f32 v184, v80, v81, v82
	s_nop 0
	v_max3_f32 v202, v64, v65, v66
	v_max3_f32 v184, v184, v83, v84
	v_max3_f32 v202, v202, v67, v68
	v_max3_f32 v184, v184, v85, v86
	v_max3_f32 v202, v202, v69, v70
	v_max3_f32 v184, v184, v87, v88
	v_max3_f32 v202, v202, v71, v72
	v_max3_f32 v184, v184, v89, v90
	v_max3_f32 v202, v202, v73, v74
	v_max3_f32 v184, v184, v91, v92
	v_max3_f32 v202, v202, v75, v76
	v_max_f32_e32 v203, v79, v79
	v_max_f32_e32 v204, v95, v95
	v_max3_f32 v184, v184, v93, v94
	v_max3_f32 v202, v202, v77, v78
	v_max_f32_e32 v203, v204, v203
	v_max3_f32 v184, v184, v202, v203
	ds_bpermute_b32 v202, v224, v184
	s_waitcnt lgkmcnt(0)
	v_max_f32_e32 v202, v202, v202
	v_max_f32_e32 v184, v184, v202
	v_cmp_lt_f32_e32 vcc, s93, v184
	s_cbranch_vccz .LBB0_160
	v_max_f32_e32 v184, v184, v184
	v_max_f32_e32 v184, 0, v184
	v_exp_f32_e64 v202, -v184
	v_add_f32_e32 v226, v226, v184
	v_pk_add_f32 v[80:81], v[80:81], v[184:185] op_sel_hi:[1,0] neg_lo:[0,1] neg_hi:[0,1]
	v_mul_f32_e32 v222, v222, v202
	v_pk_mul_f32 v[62:63], v[62:63], v[202:203] op_sel_hi:[1,0]
	v_pk_mul_f32 v[60:61], v[60:61], v[202:203] op_sel_hi:[1,0]
	v_pk_mul_f32 v[58:59], v[58:59], v[202:203] op_sel_hi:[1,0]
	v_pk_mul_f32 v[56:57], v[56:57], v[202:203] op_sel_hi:[1,0]
	v_pk_mul_f32 v[54:55], v[54:55], v[202:203] op_sel_hi:[1,0]
	v_pk_mul_f32 v[52:53], v[52:53], v[202:203] op_sel_hi:[1,0]
	v_pk_mul_f32 v[50:51], v[50:51], v[202:203] op_sel_hi:[1,0]
	v_pk_mul_f32 v[48:49], v[48:49], v[202:203] op_sel_hi:[1,0]
	v_pk_mul_f32 v[46:47], v[46:47], v[202:203] op_sel_hi:[1,0]
	v_pk_mul_f32 v[44:45], v[44:45], v[202:203] op_sel_hi:[1,0]
	v_pk_mul_f32 v[42:43], v[42:43], v[202:203] op_sel_hi:[1,0]
	v_pk_mul_f32 v[40:41], v[40:41], v[202:203] op_sel_hi:[1,0]
	v_pk_mul_f32 v[38:39], v[38:39], v[202:203] op_sel_hi:[1,0]
	v_pk_mul_f32 v[36:37], v[36:37], v[202:203] op_sel_hi:[1,0]
	v_pk_mul_f32 v[34:35], v[34:35], v[202:203] op_sel_hi:[1,0]
	v_pk_mul_f32 v[32:33], v[32:33], v[202:203] op_sel_hi:[1,0]
	v_pk_mul_f32 v[30:31], v[30:31], v[202:203] op_sel_hi:[1,0]
	v_pk_mul_f32 v[28:29], v[28:29], v[202:203] op_sel_hi:[1,0]
	v_pk_mul_f32 v[26:27], v[26:27], v[202:203] op_sel_hi:[1,0]
	v_pk_mul_f32 v[24:25], v[24:25], v[202:203] op_sel_hi:[1,0]
	v_pk_mul_f32 v[22:23], v[22:23], v[202:203] op_sel_hi:[1,0]
	v_pk_mul_f32 v[20:21], v[20:21], v[202:203] op_sel_hi:[1,0]
	v_pk_mul_f32 v[18:19], v[18:19], v[202:203] op_sel_hi:[1,0]
	v_pk_mul_f32 v[16:17], v[16:17], v[202:203] op_sel_hi:[1,0]
	v_pk_mul_f32 v[14:15], v[14:15], v[202:203] op_sel_hi:[1,0]
	v_pk_mul_f32 v[12:13], v[12:13], v[202:203] op_sel_hi:[1,0]
	v_pk_mul_f32 v[10:11], v[10:11], v[202:203] op_sel_hi:[1,0]
	v_pk_mul_f32 v[8:9], v[8:9], v[202:203] op_sel_hi:[1,0]
	v_pk_mul_f32 v[6:7], v[6:7], v[202:203] op_sel_hi:[1,0]
	v_pk_mul_f32 v[4:5], v[4:5], v[202:203] op_sel_hi:[1,0]
	v_pk_mul_f32 v[2:3], v[2:3], v[202:203] op_sel_hi:[1,0]
	v_pk_mul_f32 v[0:1], v[0:1], v[202:203] op_sel_hi:[1,0]
	v_pk_add_f32 v[64:65], v[64:65], v[184:185] op_sel_hi:[1,0] neg_lo:[0,1] neg_hi:[0,1]
	v_pk_add_f32 v[82:83], v[82:83], v[184:185] op_sel_hi:[1,0] neg_lo:[0,1] neg_hi:[0,1]
	v_pk_add_f32 v[66:67], v[66:67], v[184:185] op_sel_hi:[1,0] neg_lo:[0,1] neg_hi:[0,1]
	v_pk_add_f32 v[84:85], v[84:85], v[184:185] op_sel_hi:[1,0] neg_lo:[0,1] neg_hi:[0,1]
	v_pk_add_f32 v[68:69], v[68:69], v[184:185] op_sel_hi:[1,0] neg_lo:[0,1] neg_hi:[0,1]
	v_pk_add_f32 v[86:87], v[86:87], v[184:185] op_sel_hi:[1,0] neg_lo:[0,1] neg_hi:[0,1]
	v_pk_add_f32 v[70:71], v[70:71], v[184:185] op_sel_hi:[1,0] neg_lo:[0,1] neg_hi:[0,1]
	v_pk_add_f32 v[88:89], v[88:89], v[184:185] op_sel_hi:[1,0] neg_lo:[0,1] neg_hi:[0,1]
	v_pk_add_f32 v[72:73], v[72:73], v[184:185] op_sel_hi:[1,0] neg_lo:[0,1] neg_hi:[0,1]
	v_pk_add_f32 v[90:91], v[90:91], v[184:185] op_sel_hi:[1,0] neg_lo:[0,1] neg_hi:[0,1]
	v_pk_add_f32 v[74:75], v[74:75], v[184:185] op_sel_hi:[1,0] neg_lo:[0,1] neg_hi:[0,1]
	v_pk_add_f32 v[92:93], v[92:93], v[184:185] op_sel_hi:[1,0] neg_lo:[0,1] neg_hi:[0,1]
	v_pk_add_f32 v[76:77], v[76:77], v[184:185] op_sel_hi:[1,0] neg_lo:[0,1] neg_hi:[0,1]
	v_pk_add_f32 v[94:95], v[94:95], v[184:185] op_sel_hi:[1,0] neg_lo:[0,1] neg_hi:[0,1]
	v_pk_add_f32 v[78:79], v[78:79], v[184:185] op_sel_hi:[1,0] neg_lo:[0,1] neg_hi:[0,1]
; #define MFMA(a, b, c) __builtin_amdgcn_mfma_f32_32x32x16_bf16((a), (b), (c), 0, 0, 0)
; DI void softmax_pv(f32x16 (&sa)[2], f32x16 (&O)[4], float& m, float& l, const char* sV, int lr, int lh, bool first) {
;     ...
;   float rsum0 = 0.f, rsum1 = 0.f;
; #pragma unroll
;   for (int i = 0; i < 16; ++i) {
;     float p0 = __builtin_amdgcn_exp2f(sa[0][i]);
;     float p1 = __builtin_amdgcn_exp2f(sa[1][i]);
;     sa[0][i] = p0;
;     sa[1][i] = p1;
;     rsum0 += p0;
;     rsum1 += p1;
;   }
;   l += rsum0 + rsum1;
;   bf16x8 pf[4];
; #pragma unroll
;   for (int g4 = 0; g4 < 4; ++g4) {
;     const int kb = g4 >> 1, s2 = g4 & 1;
;     u32x4 pp;
; #pragma unroll
;     for (int j = 0; j < 4; ++j) pp[j] = pk2(sa[kb][8 * s2 + 2 * j], sa[kb][8 * s2 + 2 * j + 1]);
;     pf[g4] = __builtin_bit_cast(bf16x8, pp);
;   }
;   const char* vrd = sV + lr * 144 + lh * 16;
;   bf16x8 vfr[4];
; #pragma unroll
;   for (int t = 0; t < 3; ++t) vfr[t] = *(const bf16x8*)(vrd + (t & 3) * (32 * 144) + (t >> 2) * 32);
;   __builtin_amdgcn_sched_group_barrier(0x100, 3, 0);
; #pragma unroll
;   for (int t = 0; t < 16; ++t) {
;     if (t + 3 < 16) {
;       vfr[(t + 3) & 3] = *(const bf16x8*)(vrd + ((t + 3) & 3) * (32 * 144) + ((t + 3) >> 2) * 32);
;       __builtin_amdgcn_sched_group_barrier(0x100, 1, 0);
;     }
;     O[t & 3] = MFMA(vfr[t & 3], pf[t >> 2], O[t & 3]);
;     __builtin_amdgcn_sched_group_barrier(0x008, 1, 0);
;   }
; DI void load_vtile(u32x4 (&rv)[4], const u16* __restrict__ vbase, int Lp, int key0, unsigned voffV) {
;   const char* ub = (const char*)vbase + (long)key0 * 2;
; #pragma unroll
;   for (int i = 0; i < 4; ++i) rv[i] = *(const u32x4*)(ub + (long)(32 * i) * Lp * 2 + voffV);
; }
.LBB0_160:
	ds_read_b128 v[202:205], v225 offset:25600
	ds_read_b128 v[232:235], v225 offset:30208
	ds_read_b128 v[236:239], v225 offset:34816
	ds_read_b128 v[240:243], v225 offset:39424
	v_exp_f32_e32 v80, v80
	v_exp_f32_e32 v81, v81
	v_exp_f32_e32 v82, v82
	v_exp_f32_e32 v83, v83
	v_exp_f32_e32 v84, v84
	v_exp_f32_e32 v85, v85
	v_exp_f32_e32 v86, v86
	v_exp_f32_e32 v87, v87
	v_cvt_pk_bf16_f32 v206, v80, v81
	v_cvt_pk_bf16_f32 v207, v82, v83
	v_cvt_pk_bf16_f32 v208, v84, v85
	v_cvt_pk_bf16_f32 v209, v86, v87
	v_exp_f32_e32 v231, v89
	v_exp_f32_e32 v184, v90
	s_waitcnt lgkmcnt(3)
	v_mfma_f32_32x32x16_bf16 v[48:63], v[202:205], v[206:209], v[48:63]
	ds_read_b128 v[202:205], v225 offset:25632
	v_exp_f32_e32 v90, v91
	v_exp_f32_e32 v89, v92
	v_exp_f32_e32 v92, v94
	v_exp_f32_e32 v91, v95
	v_exp_f32_e32 v95, v64
	v_exp_f32_e32 v94, v65
	s_waitcnt lgkmcnt(3)
	v_mfma_f32_32x32x16_bf16 v[32:47], v[232:235], v[206:209], v[32:47]
	ds_read_b128 v[244:247], v225 offset:30240
	s_cmp_ge_i32 s92, s85
	s_cbranch_scc1 .Lpvm0_novl
	v_lshl_add_u64 v[152:153], v[194:195], 0, s[94:95]
	v_lshl_add_u64 v[156:157], v[152:153], 0, s[88:89]
	v_lshl_add_u64 v[164:165], v[156:157], 0, s[88:89]
	v_lshl_add_u64 v[168:169], v[164:165], 0, s[88:89]
	global_load_dwordx4 v[152:155], v[152:153], off
	global_load_dwordx4 v[156:159], v[156:157], off
	global_load_dwordx4 v[164:167], v[164:165], off
	global_load_dwordx4 v[168:171], v[168:169], off
.Lpvm0_novl:
	v_exp_f32_e32 v232, v88
	v_exp_f32_e32 v88, v93
	v_exp_f32_e32 v93, v66
	v_exp_f32_e32 v66, v67
	v_exp_f32_e32 v65, v68
	v_exp_f32_e32 v64, v69
	s_waitcnt lgkmcnt(3)
	v_mfma_f32_32x32x16_bf16 v[16:31], v[236:239], v[206:209], v[16:31]
	ds_read_b128 v[234:237], v225 offset:34848
	v_exp_f32_e32 v68, v70
	v_exp_f32_e32 v67, v71
	v_exp_f32_e32 v233, v73
	v_exp_f32_e32 v71, v75
	v_exp_f32_e32 v70, v76
	v_exp_f32_e32 v69, v77
	s_waitcnt lgkmcnt(3)
	v_mfma_f32_32x32x16_bf16 v[0:15], v[240:243], v[206:209], v[0:15]
	ds_read_b128 v[238:241], v225 offset:39456
	s_waitcnt vmcnt(9)
	ds_write_b128 v191, v[144:147]
	s_waitcnt vmcnt(8)
	ds_write_b128 v191, v[148:151] offset:6400
	s_waitcnt vmcnt(7)
	ds_write_b128 v191, v[160:163] offset:12800
	v_cvt_pk_bf16_f32 v206, v232, v231
	v_cvt_pk_bf16_f32 v207, v184, v90
	v_cvt_pk_bf16_f32 v208, v89, v88
	v_cvt_pk_bf16_f32 v209, v92, v91
	v_exp_f32_e32 v73, v79
	s_and_b64 vcc, exec, s[74:75]
	s_waitcnt lgkmcnt(6)
	v_mfma_f32_32x32x16_bf16 v[48:63], v[202:205], v[206:209], v[48:63]
	ds_read_b128 v[202:205], v225 offset:25664
	s_waitcnt lgkmcnt(6)
	v_mfma_f32_32x32x16_bf16 v[32:47], v[244:247], v[206:209], v[32:47]
	ds_read_b128 v[242:245], v225 offset:30272
	s_waitcnt lgkmcnt(6)
	v_mfma_f32_32x32x16_bf16 v[16:31], v[234:237], v[206:209], v[16:31]
	ds_read_b128 v[234:237], v225 offset:34880
	s_waitcnt lgkmcnt(6)
	v_mfma_f32_32x32x16_bf16 v[0:15], v[238:241], v[206:209], v[0:15]
	ds_read_b128 v[238:241], v225 offset:39488
	s_waitcnt vmcnt(6)
	ds_write_b128 v191, v[172:175] offset:19200
	s_waitcnt vmcnt(5)
	ds_write_b128 v193, v[176:179] offset:256
	s_waitcnt vmcnt(4)
	ds_write_b128 v193, v[180:183] offset:13056
	v_cvt_pk_bf16_f32 v206, v95, v94
	v_cvt_pk_bf16_f32 v207, v93, v66
	v_cvt_pk_bf16_f32 v208, v65, v64
	v_cvt_pk_bf16_f32 v209, v68, v67
	s_waitcnt lgkmcnt(6)
	s_nop 0
	v_mfma_f32_32x32x16_bf16 v[48:63], v[202:205], v[206:209], v[48:63]
	ds_read_b128 v[202:205], v225 offset:25696
	s_waitcnt lgkmcnt(6)
	v_mfma_f32_32x32x16_bf16 v[32:47], v[242:245], v[206:209], v[32:47]
	ds_read_b128 v[242:245], v225 offset:30304
	s_waitcnt lgkmcnt(6)
	v_mfma_f32_32x32x16_bf16 v[16:31], v[234:237], v[206:209], v[16:31]
	ds_read_b128 v[246:249], v225 offset:34912
	v_exp_f32_e32 v234, v72
	v_exp_f32_e32 v72, v74
	v_exp_f32_e32 v74, v78
	v_cvt_pk_bf16_f32 v78, v70, v69
	v_cvt_pk_bf16_f32 v76, v234, v233
	v_cvt_pk_bf16_f32 v77, v72, v71
	s_waitcnt lgkmcnt(6)
	v_mfma_f32_32x32x16_bf16 v[0:15], v[238:241], v[206:209], v[0:15]
	ds_read_b128 v[206:209], v225 offset:39520
	v_cvt_pk_bf16_f32 v79, v74, v73
	s_waitcnt lgkmcnt(0)
	s_barrier
	v_mfma_f32_32x32x16_bf16 v[48:63], v[202:205], v[76:79], v[48:63]
	v_mfma_f32_32x32x16_bf16 v[32:47], v[242:245], v[76:79], v[32:47]
	v_mfma_f32_32x32x16_bf16 v[16:31], v[246:249], v[76:79], v[16:31]
	v_mfma_f32_32x32x16_bf16 v[0:15], v[206:209], v[76:79], v[0:15]
	s_branch .LBB0_151

; DI void softmax_pv(f32x16 (&sa)[2], f32x16 (&O)[4], float& m, float& l, const char* sV, int lr, int lh, bool first) {
;   float t0 = fmaxf(fmaxf(sa[0][0], sa[0][1]), sa[0][2]);
;   float t1 = fmaxf(fmaxf(sa[1][0], sa[1][1]), sa[1][2]);
; #pragma unroll
;   for (int i = 3; i < 15; i += 2) {
;     t0 = fmaxf(fmaxf(t0, sa[0][i]), sa[0][i + 1]);
;     t1 = fmaxf(fmaxf(t1, sa[1][i]), sa[1][i + 1]);
;   }
;   float tmax = fmaxf(fmaxf(t0, t1), fmaxf(sa[0][15], sa[1][15]));
;   tmax = fmaxf(tmax, __shfl_xor(tmax, 32, 64));
;   if (first || __any(tmax > SM_THR)) {
;     asm volatile("; rescale" ::: "memory");
;     const float delta = first ? tmax : fmaxf(tmax, 0.f);
;     const float alpha = __builtin_amdgcn_exp2f(-delta);
;     m += delta;
;     l *= alpha;
; #pragma unroll
;     for (int d = 0; d < 4; ++d)
; #pragma unroll
;       for (int i = 0; i < 16; ++i) O[d][i] *= alpha;
; #pragma unroll
;     for (int i = 0; i < 16; ++i) { sa[0][i] -= delta; sa[1][i] -= delta; }
;   }
;   float rsum0 = 0.f, rsum1 = 0.f;
; #pragma unroll
;   for (int i = 0; i < 16; ++i) {
;     float p0 = __builtin_amdgcn_exp2f(sa[0][i]);
;     float p1 = __builtin_amdgcn_exp2f(sa[1][i]);
;     sa[0][i] = p0;
;     sa[1][i] = p1;
;     rsum0 += p0;
;     rsum1 += p1;
;   }
;   l += rsum0 + rsum1;
;   bf16x8 pf[4];
; #pragma unroll
;   for (int g4 = 0; g4 < 4; ++g4) {
;     const int kb = g4 >> 1, s2 = g4 & 1;
;     u32x4 pp;
; #pragma unroll
;     for (int j = 0; j < 4; ++j) pp[j] = pk2(sa[kb][8 * s2 + 2 * j], sa[kb][8 * s2 + 2 * j + 1]);
;     pf[g4] = __builtin_bit_cast(bf16x8, pp);
;   }
;   const char* vrd = sV + lr * 144 + lh * 16;
;   bf16x8 vfr[4];
; #pragma unroll
;   for (int t = 0; t < 3; ++t) vfr[t] = *(const bf16x8*)(vrd + (t & 3) * (32 * 144) + (t >> 2) * 32);
;   __builtin_amdgcn_sched_group_barrier(0x100, 3, 0);
; #pragma unroll
;   for (int t = 0; t < 16; ++t) {
;     if (t + 3 < 16) {
;       vfr[(t + 3) & 3] = *(const bf16x8*)(vrd + ((t + 3) & 3) * (32 * 144) + ((t + 3) >> 2) * 32);
;       __builtin_amdgcn_sched_group_barrier(0x100, 1, 0);
;     }
;     O[t & 3] = MFMA(vfr[t & 3], pf[t >> 2], O[t & 3]);
;     __builtin_amdgcn_sched_group_barrier(0x008, 1, 0);
;   }
; DI void diff_item(const Params& p, const GroupP& g, int l_layer, int item, char* smem, bool dry) {
;     ...
;     __syncthreads();
;     if (more) { storeK(); load_vtile(rv, vbase, Lp, (kt + 1) * 64, voffV); }
.LBB0_200:
	v_cndmask_b32_e64 v172, 0, 1, s[40:41]
	v_cmp_ne_u32_e64 s[8:9], 1, v172
	s_andn2_b64 vcc, exec, s[40:41]
	s_barrier
	s_cbranch_vccnz .LBB0_202
.LBB0_202:
	v_max3_f32 v172, v80, v81, v82
	s_nop 1
	v_max3_f32 v173, v64, v65, v66
	v_max3_f32 v172, v172, v83, v84
	v_max3_f32 v173, v173, v67, v68
	v_max3_f32 v172, v172, v85, v86
	v_max3_f32 v173, v173, v69, v70
	v_max3_f32 v172, v172, v87, v88
	v_max3_f32 v173, v173, v71, v72
	v_max3_f32 v172, v172, v89, v90
	v_max3_f32 v173, v173, v73, v74
	v_max3_f32 v172, v172, v91, v92
	v_max3_f32 v173, v173, v75, v76
	v_max_f32_e32 v174, v79, v79
	v_max_f32_e32 v175, v95, v95
	v_max3_f32 v172, v172, v93, v94
	v_max3_f32 v173, v173, v77, v78
	v_max_f32_e32 v174, v175, v174
	v_max3_f32 v172, v172, v173, v174
	ds_bpermute_b32 v173, v164, v172
	s_mov_b32 s10, 0x41000000
	s_waitcnt lgkmcnt(0)
	v_max_f32_e32 v173, v173, v173
	v_max_f32_e32 v172, v172, v173
	v_cmp_lt_f32_e32 vcc, s10, v172
	s_cbranch_vccz .LBB0_204
	v_max_f32_e32 v172, v172, v172
	v_max_f32_e32 v172, 0, v172
	v_exp_f32_e64 v174, -v172
	v_add_f32_e32 v166, v166, v172
	v_pk_add_f32 v[80:81], v[80:81], v[172:173] op_sel_hi:[1,0] neg_lo:[0,1] neg_hi:[0,1]
	v_mul_f32_e32 v163, v163, v174
	v_pk_mul_f32 v[62:63], v[62:63], v[174:175] op_sel_hi:[1,0]
	v_pk_mul_f32 v[60:61], v[60:61], v[174:175] op_sel_hi:[1,0]
	v_pk_mul_f32 v[58:59], v[58:59], v[174:175] op_sel_hi:[1,0]
	v_pk_mul_f32 v[56:57], v[56:57], v[174:175] op_sel_hi:[1,0]
	v_pk_mul_f32 v[54:55], v[54:55], v[174:175] op_sel_hi:[1,0]
	v_pk_mul_f32 v[52:53], v[52:53], v[174:175] op_sel_hi:[1,0]
	v_pk_mul_f32 v[50:51], v[50:51], v[174:175] op_sel_hi:[1,0]
	v_pk_mul_f32 v[48:49], v[48:49], v[174:175] op_sel_hi:[1,0]
	v_pk_mul_f32 v[46:47], v[46:47], v[174:175] op_sel_hi:[1,0]
	v_pk_mul_f32 v[44:45], v[44:45], v[174:175] op_sel_hi:[1,0]
	v_pk_mul_f32 v[42:43], v[42:43], v[174:175] op_sel_hi:[1,0]
	v_pk_mul_f32 v[40:41], v[40:41], v[174:175] op_sel_hi:[1,0]
	v_pk_mul_f32 v[38:39], v[38:39], v[174:175] op_sel_hi:[1,0]
	v_pk_mul_f32 v[36:37], v[36:37], v[174:175] op_sel_hi:[1,0]
	v_pk_mul_f32 v[34:35], v[34:35], v[174:175] op_sel_hi:[1,0]
	v_pk_mul_f32 v[32:33], v[32:33], v[174:175] op_sel_hi:[1,0]
	v_pk_mul_f32 v[30:31], v[30:31], v[174:175] op_sel_hi:[1,0]
	v_pk_mul_f32 v[28:29], v[28:29], v[174:175] op_sel_hi:[1,0]
	v_pk_mul_f32 v[26:27], v[26:27], v[174:175] op_sel_hi:[1,0]
	v_pk_mul_f32 v[24:25], v[24:25], v[174:175] op_sel_hi:[1,0]
	v_pk_mul_f32 v[22:23], v[22:23], v[174:175] op_sel_hi:[1,0]
	v_pk_mul_f32 v[20:21], v[20:21], v[174:175] op_sel_hi:[1,0]
	v_pk_mul_f32 v[18:19], v[18:19], v[174:175] op_sel_hi:[1,0]
	v_pk_mul_f32 v[16:17], v[16:17], v[174:175] op_sel_hi:[1,0]
	v_pk_mul_f32 v[14:15], v[14:15], v[174:175] op_sel_hi:[1,0]
	v_pk_mul_f32 v[12:13], v[12:13], v[174:175] op_sel_hi:[1,0]
	v_pk_mul_f32 v[10:11], v[10:11], v[174:175] op_sel_hi:[1,0]
	v_pk_mul_f32 v[8:9], v[8:9], v[174:175] op_sel_hi:[1,0]
	v_pk_mul_f32 v[6:7], v[6:7], v[174:175] op_sel_hi:[1,0]
	v_pk_mul_f32 v[4:5], v[4:5], v[174:175] op_sel_hi:[1,0]
	v_pk_mul_f32 v[2:3], v[2:3], v[174:175] op_sel_hi:[1,0]
	v_pk_mul_f32 v[0:1], v[0:1], v[174:175] op_sel_hi:[1,0]
	v_pk_add_f32 v[64:65], v[64:65], v[172:173] op_sel_hi:[1,0] neg_lo:[0,1] neg_hi:[0,1]
	v_pk_add_f32 v[82:83], v[82:83], v[172:173] op_sel_hi:[1,0] neg_lo:[0,1] neg_hi:[0,1]
	v_pk_add_f32 v[66:67], v[66:67], v[172:173] op_sel_hi:[1,0] neg_lo:[0,1] neg_hi:[0,1]
	v_pk_add_f32 v[84:85], v[84:85], v[172:173] op_sel_hi:[1,0] neg_lo:[0,1] neg_hi:[0,1]
	v_pk_add_f32 v[68:69], v[68:69], v[172:173] op_sel_hi:[1,0] neg_lo:[0,1] neg_hi:[0,1]
	v_pk_add_f32 v[86:87], v[86:87], v[172:173] op_sel_hi:[1,0] neg_lo:[0,1] neg_hi:[0,1]
	v_pk_add_f32 v[70:71], v[70:71], v[172:173] op_sel_hi:[1,0] neg_lo:[0,1] neg_hi:[0,1]
	v_pk_add_f32 v[88:89], v[88:89], v[172:173] op_sel_hi:[1,0] neg_lo:[0,1] neg_hi:[0,1]
	v_pk_add_f32 v[72:73], v[72:73], v[172:173] op_sel_hi:[1,0] neg_lo:[0,1] neg_hi:[0,1]
	v_pk_add_f32 v[90:91], v[90:91], v[172:173] op_sel_hi:[1,0] neg_lo:[0,1] neg_hi:[0,1]
	v_pk_add_f32 v[74:75], v[74:75], v[172:173] op_sel_hi:[1,0] neg_lo:[0,1] neg_hi:[0,1]
	v_pk_add_f32 v[92:93], v[92:93], v[172:173] op_sel_hi:[1,0] neg_lo:[0,1] neg_hi:[0,1]
	v_pk_add_f32 v[76:77], v[76:77], v[172:173] op_sel_hi:[1,0] neg_lo:[0,1] neg_hi:[0,1]
	v_pk_add_f32 v[94:95], v[94:95], v[172:173] op_sel_hi:[1,0] neg_lo:[0,1] neg_hi:[0,1]
	v_pk_add_f32 v[78:79], v[78:79], v[172:173] op_sel_hi:[1,0] neg_lo:[0,1] neg_hi:[0,1]
.LBB0_204:
	ds_read_b128 v[192:195], v165 offset:17408
	ds_read_b128 v[196:199], v165 offset:22016
	ds_read_b128 v[202:205], v165 offset:26624
	ds_read_b128 v[206:209], v165 offset:31232
	v_exp_f32_e32 v80, v80
	v_exp_f32_e32 v81, v81
	v_exp_f32_e32 v82, v82
	v_exp_f32_e32 v83, v83
	v_exp_f32_e32 v84, v84
	v_exp_f32_e32 v85, v85
	v_exp_f32_e32 v86, v86
	v_exp_f32_e32 v87, v87
	v_cvt_pk_bf16_f32 v188, v80, v81
	v_cvt_pk_bf16_f32 v189, v82, v83
	v_cvt_pk_bf16_f32 v190, v84, v85
	v_cvt_pk_bf16_f32 v191, v86, v87
	v_exp_f32_e32 v88, v88
	v_exp_f32_e32 v89, v89
	s_waitcnt lgkmcnt(3)
	v_mfma_f32_32x32x16_bf16 v[48:63], v[192:195], v[188:191], v[48:63]
	ds_read_b128 v[192:195], v165 offset:17440
	v_exp_f32_e32 v90, v90
	v_exp_f32_e32 v91, v91
	v_exp_f32_e32 v92, v92
	v_exp_f32_e32 v93, v93
	v_exp_f32_e32 v94, v94
	v_exp_f32_e32 v95, v95
	s_waitcnt lgkmcnt(3)
	v_mfma_f32_32x32x16_bf16 v[32:47], v[196:199], v[188:191], v[32:47]
	ds_read_b128 v[196:199], v165 offset:22048
	s_add_i32 s100, s42, 2
	s_cmp_ge_i32 s100, s33
	s_cbranch_scc1 .Lpvd1_novl
	v_lshl_add_u64 v[120:121], v[150:151], 0, s[94:95]
	v_lshl_add_u64 v[124:125], v[120:121], 0, s[96:97]
	v_lshl_add_u64 v[128:129], v[124:125], 0, s[96:97]
	v_lshl_add_u64 v[132:133], v[128:129], 0, s[96:97]
	global_load_dwordx4 v[120:123], v[120:121], off
	global_load_dwordx4 v[124:127], v[124:125], off
	global_load_dwordx4 v[128:131], v[128:129], off
	global_load_dwordx4 v[132:135], v[132:133], off

; DI void softmax_pv(f32x16 (&sa)[2], f32x16 (&O)[4], float& m, float& l, const char* sV, int lr, int lh, bool first) {
;   float t0 = fmaxf(fmaxf(sa[0][0], sa[0][1]), sa[0][2]);
;   float t1 = fmaxf(fmaxf(sa[1][0], sa[1][1]), sa[1][2]);
; #pragma unroll
;   for (int i = 3; i < 15; i += 2) {
;     t0 = fmaxf(fmaxf(t0, sa[0][i]), sa[0][i + 1]);
;     t1 = fmaxf(fmaxf(t1, sa[1][i]), sa[1][i + 1]);
;   }
;   float tmax = fmaxf(fmaxf(t0, t1), fmaxf(sa[0][15], sa[1][15]));
;   tmax = fmaxf(tmax, __shfl_xor(tmax, 32, 64));
;   if (first || __any(tmax > SM_THR)) {
;     asm volatile("; rescale" ::: "memory");
;     const float delta = first ? tmax : fmaxf(tmax, 0.f);
;     const float alpha = __builtin_amdgcn_exp2f(-delta);
;     m += delta;
;     l *= alpha;
; #pragma unroll
;     for (int d = 0; d < 4; ++d)
; #pragma unroll
;       for (int i = 0; i < 16; ++i) O[d][i] *= alpha;
; #pragma unroll
;     for (int i = 0; i < 16; ++i) { sa[0][i] -= delta; sa[1][i] -= delta; }
;   }
; DI void mla_item(const Params& p, const GroupP& g, int item, char* smem, bool dry) {
;     ...
;     __syncthreads();
;     if (more) { storeK(); load_vtile(rv, vbase, Lp, (kt + 1) * 64, voffV); }
.LBB0_229:
	v_cndmask_b32_e64 v184, 0, 1, s[4:5]
	v_cmp_ne_u32_e64 s[74:75], 1, v184
	s_andn2_b64 vcc, exec, s[4:5]
	s_barrier
	s_cbranch_vccnz .LBB0_231
.LBB0_231:
	s_nop 3
	v_max3_f32 v184, v80, v81, v82
	s_nop 0
	v_max3_f32 v202, v64, v65, v66
	v_max3_f32 v184, v184, v83, v84
	v_max3_f32 v202, v202, v67, v68
	v_max3_f32 v184, v184, v85, v86
	v_max3_f32 v202, v202, v69, v70
	v_max3_f32 v184, v184, v87, v88
	v_max3_f32 v202, v202, v71, v72
	v_max3_f32 v184, v184, v89, v90
	v_max3_f32 v202, v202, v73, v74
	v_max3_f32 v184, v184, v91, v92
	v_max3_f32 v202, v202, v75, v76
	v_max_f32_e32 v203, v79, v79
	v_max_f32_e32 v204, v95, v95
	v_max3_f32 v184, v184, v93, v94
	v_max3_f32 v202, v202, v77, v78
	v_max_f32_e32 v203, v204, v203
	v_max3_f32 v184, v184, v202, v203
	ds_bpermute_b32 v202, v224, v184
	s_waitcnt lgkmcnt(0)
	v_max_f32_e32 v202, v202, v202
	v_max_f32_e32 v184, v184, v202
	v_cmp_lt_f32_e32 vcc, s87, v184
	s_cbranch_vccz .LBB0_233
	v_max_f32_e32 v184, v184, v184
	v_max_f32_e32 v184, 0, v184
	v_exp_f32_e64 v202, -v184
	v_add_f32_e32 v226, v226, v184
	v_pk_add_f32 v[80:81], v[80:81], v[184:185] op_sel_hi:[1,0] neg_lo:[0,1] neg_hi:[0,1]
	v_mul_f32_e32 v222, v222, v202
	v_pk_mul_f32 v[62:63], v[62:63], v[202:203] op_sel_hi:[1,0]
	v_pk_mul_f32 v[60:61], v[60:61], v[202:203] op_sel_hi:[1,0]
	v_pk_mul_f32 v[58:59], v[58:59], v[202:203] op_sel_hi:[1,0]
	v_pk_mul_f32 v[56:57], v[56:57], v[202:203] op_sel_hi:[1,0]
	v_pk_mul_f32 v[54:55], v[54:55], v[202:203] op_sel_hi:[1,0]
	v_pk_mul_f32 v[52:53], v[52:53], v[202:203] op_sel_hi:[1,0]
	v_pk_mul_f32 v[50:51], v[50:51], v[202:203] op_sel_hi:[1,0]
	v_pk_mul_f32 v[48:49], v[48:49], v[202:203] op_sel_hi:[1,0]
	v_pk_mul_f32 v[46:47], v[46:47], v[202:203] op_sel_hi:[1,0]
	v_pk_mul_f32 v[44:45], v[44:45], v[202:203] op_sel_hi:[1,0]
	v_pk_mul_f32 v[42:43], v[42:43], v[202:203] op_sel_hi:[1,0]
	v_pk_mul_f32 v[40:41], v[40:41], v[202:203] op_sel_hi:[1,0]
	v_pk_mul_f32 v[38:39], v[38:39], v[202:203] op_sel_hi:[1,0]
	v_pk_mul_f32 v[36:37], v[36:37], v[202:203] op_sel_hi:[1,0]
	v_pk_mul_f32 v[34:35], v[34:35], v[202:203] op_sel_hi:[1,0]
	v_pk_mul_f32 v[32:33], v[32:33], v[202:203] op_sel_hi:[1,0]
	v_pk_mul_f32 v[30:31], v[30:31], v[202:203] op_sel_hi:[1,0]
	v_pk_mul_f32 v[28:29], v[28:29], v[202:203] op_sel_hi:[1,0]
	v_pk_mul_f32 v[26:27], v[26:27], v[202:203] op_sel_hi:[1,0]
	v_pk_mul_f32 v[24:25], v[24:25], v[202:203] op_sel_hi:[1,0]
	v_pk_mul_f32 v[22:23], v[22:23], v[202:203] op_sel_hi:[1,0]
	v_pk_mul_f32 v[20:21], v[20:21], v[202:203] op_sel_hi:[1,0]
	v_pk_mul_f32 v[18:19], v[18:19], v[202:203] op_sel_hi:[1,0]
	v_pk_mul_f32 v[16:17], v[16:17], v[202:203] op_sel_hi:[1,0]
	v_pk_mul_f32 v[14:15], v[14:15], v[202:203] op_sel_hi:[1,0]
	v_pk_mul_f32 v[12:13], v[12:13], v[202:203] op_sel_hi:[1,0]
	v_pk_mul_f32 v[10:11], v[10:11], v[202:203] op_sel_hi:[1,0]
	v_pk_mul_f32 v[8:9], v[8:9], v[202:203] op_sel_hi:[1,0]
	v_pk_mul_f32 v[6:7], v[6:7], v[202:203] op_sel_hi:[1,0]
	v_pk_mul_f32 v[4:5], v[4:5], v[202:203] op_sel_hi:[1,0]
	v_pk_mul_f32 v[2:3], v[2:3], v[202:203] op_sel_hi:[1,0]
	v_pk_mul_f32 v[0:1], v[0:1], v[202:203] op_sel_hi:[1,0]
	v_pk_add_f32 v[64:65], v[64:65], v[184:185] op_sel_hi:[1,0] neg_lo:[0,1] neg_hi:[0,1]
	v_pk_add_f32 v[82:83], v[82:83], v[184:185] op_sel_hi:[1,0] neg_lo:[0,1] neg_hi:[0,1]
	v_pk_add_f32 v[66:67], v[66:67], v[184:185] op_sel_hi:[1,0] neg_lo:[0,1] neg_hi:[0,1]
	v_pk_add_f32 v[84:85], v[84:85], v[184:185] op_sel_hi:[1,0] neg_lo:[0,1] neg_hi:[0,1]
	v_pk_add_f32 v[68:69], v[68:69], v[184:185] op_sel_hi:[1,0] neg_lo:[0,1] neg_hi:[0,1]
	v_pk_add_f32 v[86:87], v[86:87], v[184:185] op_sel_hi:[1,0] neg_lo:[0,1] neg_hi:[0,1]
	v_pk_add_f32 v[70:71], v[70:71], v[184:185] op_sel_hi:[1,0] neg_lo:[0,1] neg_hi:[0,1]
	v_pk_add_f32 v[88:89], v[88:89], v[184:185] op_sel_hi:[1,0] neg_lo:[0,1] neg_hi:[0,1]
	v_pk_add_f32 v[72:73], v[72:73], v[184:185] op_sel_hi:[1,0] neg_lo:[0,1] neg_hi:[0,1]
	v_pk_add_f32 v[90:91], v[90:91], v[184:185] op_sel_hi:[1,0] neg_lo:[0,1] neg_hi:[0,1]
	v_pk_add_f32 v[74:75], v[74:75], v[184:185] op_sel_hi:[1,0] neg_lo:[0,1] neg_hi:[0,1]
	v_pk_add_f32 v[92:93], v[92:93], v[184:185] op_sel_hi:[1,0] neg_lo:[0,1] neg_hi:[0,1]
	v_pk_add_f32 v[76:77], v[76:77], v[184:185] op_sel_hi:[1,0] neg_lo:[0,1] neg_hi:[0,1]
	v_pk_add_f32 v[94:95], v[94:95], v[184:185] op_sel_hi:[1,0] neg_lo:[0,1] neg_hi:[0,1]
	v_pk_add_f32 v[78:79], v[78:79], v[184:185] op_sel_hi:[1,0] neg_lo:[0,1] neg_hi:[0,1]
; #define MFMA(a, b, c) __builtin_amdgcn_mfma_f32_32x32x16_bf16((a), (b), (c), 0, 0, 0)
; DI void softmax_pv(f32x16 (&sa)[2], f32x16 (&O)[4], float& m, float& l, const char* sV, int lr, int lh, bool first) {
;     ...
;   float rsum0 = 0.f, rsum1 = 0.f;
; #pragma unroll
;   for (int i = 0; i < 16; ++i) {
;     float p0 = __builtin_amdgcn_exp2f(sa[0][i]);
;     float p1 = __builtin_amdgcn_exp2f(sa[1][i]);
;     sa[0][i] = p0;
;     sa[1][i] = p1;
;     rsum0 += p0;
;     rsum1 += p1;
;   }
;   l += rsum0 + rsum1;
;   bf16x8 pf[4];
; #pragma unroll
;   for (int g4 = 0; g4 < 4; ++g4) {
;     const int kb = g4 >> 1, s2 = g4 & 1;
;     u32x4 pp;
; #pragma unroll
;     for (int j = 0; j < 4; ++j) pp[j] = pk2(sa[kb][8 * s2 + 2 * j], sa[kb][8 * s2 + 2 * j + 1]);
;     pf[g4] = __builtin_bit_cast(bf16x8, pp);
;   }
;   const char* vrd = sV + lr * 144 + lh * 16;
;   bf16x8 vfr[4];
; #pragma unroll
;   for (int t = 0; t < 3; ++t) vfr[t] = *(const bf16x8*)(vrd + (t & 3) * (32 * 144) + (t >> 2) * 32);
;   __builtin_amdgcn_sched_group_barrier(0x100, 3, 0);
; #pragma unroll
;   for (int t = 0; t < 16; ++t) {
;     if (t + 3 < 16) {
;       vfr[(t + 3) & 3] = *(const bf16x8*)(vrd + ((t + 3) & 3) * (32 * 144) + ((t + 3) >> 2) * 32);
;       __builtin_amdgcn_sched_group_barrier(0x100, 1, 0);
;     }
;     O[t & 3] = MFMA(vfr[t & 3], pf[t >> 2], O[t & 3]);
;     __builtin_amdgcn_sched_group_barrier(0x008, 1, 0);
;   }
; DI void load_vtile(u32x4 (&rv)[4], const u16* __restrict__ vbase, int Lp, int key0, unsigned voffV) {
;   const char* ub = (const char*)vbase + (long)key0 * 2;
; #pragma unroll
;   for (int i = 0; i < 4; ++i) rv[i] = *(const u32x4*)(ub + (long)(32 * i) * Lp * 2 + voffV);
; }
.LBB0_233:
	ds_read_b128 v[206:209], v225 offset:25600
	ds_read_b128 v[238:241], v225 offset:30208
	ds_read_b128 v[242:245], v225 offset:34816
	ds_read_b128 v[246:249], v225 offset:39424
	v_exp_f32_e32 v80, v80
	v_exp_f32_e32 v81, v81
	v_exp_f32_e32 v82, v82
	v_exp_f32_e32 v83, v83
	v_exp_f32_e32 v84, v84
	v_exp_f32_e32 v85, v85
	v_exp_f32_e32 v86, v86
	v_exp_f32_e32 v87, v87
	v_cvt_pk_bf16_f32 v234, v80, v81
	v_cvt_pk_bf16_f32 v235, v82, v83
	v_cvt_pk_bf16_f32 v236, v84, v85
	v_cvt_pk_bf16_f32 v237, v86, v87
	v_exp_f32_e32 v232, v88
	v_exp_f32_e32 v231, v89
	s_waitcnt lgkmcnt(3)
	v_mfma_f32_32x32x16_bf16 v[48:63], v[206:209], v[234:237], v[48:63]
	ds_read_b128 v[206:209], v225 offset:25632
	v_exp_f32_e32 v184, v90
	v_exp_f32_e32 v90, v91
	v_exp_f32_e32 v89, v92
	v_exp_f32_e32 v88, v93
	v_exp_f32_e32 v92, v94
	v_exp_f32_e32 v91, v95
	s_waitcnt lgkmcnt(3)
	v_mfma_f32_32x32x16_bf16 v[32:47], v[238:241], v[234:237], v[32:47]
	ds_read_b128 v[238:241], v225 offset:30240
	s_cmp_ge_i32 s92, s33
	s_cbranch_scc1 .Lpvm1_novl
	v_lshl_add_u64 v[152:153], v[194:195], 0, s[94:95]
	v_lshl_add_u64 v[156:157], v[152:153], 0, s[96:97]
	v_lshl_add_u64 v[164:165], v[156:157], 0, s[96:97]
	v_lshl_add_u64 v[168:169], v[164:165], 0, s[96:97]
	global_load_dwordx4 v[152:155], v[152:153], off
	global_load_dwordx4 v[156:159], v[156:157], off
	global_load_dwordx4 v[164:167], v[164:165], off
	global_load_dwordx4 v[168:171], v[168:169], off
.Lpvm1_novl:
	v_exp_f32_e32 v95, v64
	v_exp_f32_e32 v94, v65
	v_exp_f32_e32 v93, v66
	v_exp_f32_e32 v66, v67
	v_exp_f32_e32 v65, v68
	v_exp_f32_e32 v64, v69
	s_waitcnt lgkmcnt(3)
	v_mfma_f32_32x32x16_bf16 v[16:31], v[242:245], v[234:237], v[16:31]
	ds_read_b128 v[242:245], v225 offset:34848
	v_exp_f32_e32 v68, v70
	v_exp_f32_e32 v67, v71
	v_exp_f32_e32 v233, v73
	v_exp_f32_e32 v71, v75
	v_exp_f32_e32 v70, v76
	v_exp_f32_e32 v69, v77
	s_waitcnt lgkmcnt(3)
	v_mfma_f32_32x32x16_bf16 v[0:15], v[246:249], v[234:237], v[0:15]
	ds_read_b128 v[246:249], v225 offset:39456
	s_waitcnt vmcnt(9)
	ds_write_b128 v191, v[144:147]
	s_waitcnt vmcnt(8)
	ds_write_b128 v191, v[148:151] offset:6400
	s_waitcnt vmcnt(7)
	ds_write_b128 v191, v[160:163] offset:12800
	v_cvt_pk_bf16_f32 v234, v232, v231
	v_cvt_pk_bf16_f32 v235, v184, v90
	v_cvt_pk_bf16_f32 v236, v89, v88
	v_cvt_pk_bf16_f32 v237, v92, v91
	v_exp_f32_e32 v73, v79
	s_and_b64 vcc, exec, s[74:75]
	s_waitcnt lgkmcnt(6)
	v_mfma_f32_32x32x16_bf16 v[48:63], v[206:209], v[234:237], v[48:63]
	ds_read_b128 v[206:209], v225 offset:25664
	s_waitcnt lgkmcnt(6)
	v_mfma_f32_32x32x16_bf16 v[32:47], v[238:241], v[234:237], v[32:47]
	ds_read_b128 v[238:241], v225 offset:30272
	s_waitcnt lgkmcnt(6)
	v_mfma_f32_32x32x16_bf16 v[16:31], v[242:245], v[234:237], v[16:31]
	ds_read_b128 v[242:245], v225 offset:34880
	s_waitcnt lgkmcnt(6)
	v_mfma_f32_32x32x16_bf16 v[0:15], v[246:249], v[234:237], v[0:15]
	ds_read_b128 v[202:205], v225 offset:39488
	s_waitcnt vmcnt(6)
	ds_write_b128 v191, v[172:175] offset:19200
	s_waitcnt vmcnt(5)
	ds_write_b128 v193, v[176:179] offset:256
	s_waitcnt vmcnt(4)
	ds_write_b128 v193, v[180:183] offset:13056
	v_cvt_pk_bf16_f32 v246, v95, v94
	v_cvt_pk_bf16_f32 v247, v93, v66
	v_cvt_pk_bf16_f32 v248, v65, v64
	v_cvt_pk_bf16_f32 v249, v68, v67
	v_exp_f32_e32 v234, v72
	v_exp_f32_e32 v72, v74
	s_waitcnt lgkmcnt(6)
	v_mfma_f32_32x32x16_bf16 v[48:63], v[206:209], v[246:249], v[48:63]
	ds_read_b128 v[206:209], v225 offset:25696
	v_exp_f32_e32 v74, v78
	v_cvt_pk_bf16_f32 v76, v234, v233
	v_cvt_pk_bf16_f32 v77, v72, v71
	v_cvt_pk_bf16_f32 v78, v70, v69
	v_cvt_pk_bf16_f32 v79, v74, v73
	s_waitcnt lgkmcnt(6)
	v_mfma_f32_32x32x16_bf16 v[32:47], v[238:241], v[246:249], v[32:47]
	ds_read_b128 v[236:239], v225 offset:30304
	s_waitcnt lgkmcnt(6)
	v_mfma_f32_32x32x16_bf16 v[16:31], v[242:245], v[246:249], v[16:31]
	ds_read_b128 v[240:243], v225 offset:34912
	s_waitcnt lgkmcnt(6)
	v_mfma_f32_32x32x16_bf16 v[0:15], v[202:205], v[246:249], v[0:15]
	ds_read_b128 v[202:205], v225 offset:39520
	s_waitcnt lgkmcnt(0)
	s_barrier
	v_mfma_f32_32x32x16_bf16 v[48:63], v[206:209], v[76:79], v[48:63]
	v_mfma_f32_32x32x16_bf16 v[32:47], v[236:239], v[76:79], v[32:47]
	v_mfma_f32_32x32x16_bf16 v[16:31], v[240:243], v[76:79], v[16:31]
	v_mfma_f32_32x32x16_bf16 v[0:15], v[202:205], v[76:79], v[0:15]
	s_branch .LBB0_224
